# weight-conversion prologue: next item's load waits moved behind the current item's store section; gain-path LDS round trips batched 16 at a time
# baseline (speedup 1.0000x reference)
; #define LAS __attribute__((address_space(3)))
; __device__ __forceinline__ void tr_put_gain(const float (&v)[32], LAS float* scr, int lane, const LAS float* gk) {
; #pragma unroll
;     for (int i = 0; i < 32; ++i) scr[(2 * i + (lane >> 5)) * 33 + (lane & 31)] = v[i] * gk[2 * i + (lane >> 5)];
; }
; __device__ __forceinline__ void prologue_phase(LAS unsigned char* lds) {
;     ...
;             if (g) { SG[lane] = gv; tr_put_gain(v, scr, lane, SG); } else tr_put(v, scr, lane);
.LBB0_41:
	ds_write_b32 v40, v46 offset:8448
	ds_read_b32 v76, v41 offset:8448
	ds_read_b32 v77, v41 offset:8456
	ds_read_b32 v78, v41 offset:8464
	ds_read_b32 v79, v41 offset:8472
	ds_read_b32 v80, v41 offset:8480
	ds_read_b32 v81, v41 offset:8488
	ds_read_b32 v82, v41 offset:8496
	ds_read_b32 v83, v41 offset:8504
	ds_read_b32 v84, v41 offset:8512
	ds_read_b32 v85, v41 offset:8520
	ds_read_b32 v86, v41 offset:8528
	ds_read_b32 v87, v41 offset:8536
	ds_read_b32 v88, v41 offset:8544
	ds_read_b32 v89, v41 offset:8552
	ds_read_b32 v90, v41 offset:8560
	ds_read_b32 v91, v41 offset:8568
	s_waitcnt lgkmcnt(0)
	v_mul_f32_e32 v76, v2, v76
	v_mul_f32_e32 v77, v1, v77
	v_mul_f32_e32 v78, v4, v78
	v_mul_f32_e32 v79, v3, v79
	v_mul_f32_e32 v80, v6, v80
	v_mul_f32_e32 v81, v5, v81
	v_mul_f32_e32 v82, v8, v82
	v_mul_f32_e32 v83, v7, v83
	v_mul_f32_e32 v84, v10, v84
	v_mul_f32_e32 v85, v9, v85
	v_mul_f32_e32 v86, v12, v86
	v_mul_f32_e32 v87, v11, v87
	v_mul_f32_e32 v88, v14, v88
	v_mul_f32_e32 v89, v13, v89
	v_mul_f32_e32 v90, v16, v90
	v_mul_f32_e32 v91, v15, v91
	ds_write_b32 v45, v76
	ds_write_b32 v45, v77 offset:264
	ds_write_b32 v45, v78 offset:528
	ds_write_b32 v45, v79 offset:792
	ds_write_b32 v45, v80 offset:1056
	ds_write_b32 v45, v81 offset:1320
	ds_write_b32 v45, v82 offset:1584
	ds_write_b32 v45, v83 offset:1848
	ds_write_b32 v45, v84 offset:2112
	ds_write_b32 v45, v85 offset:2376
	ds_write_b32 v45, v86 offset:2640
	ds_write_b32 v45, v87 offset:2904
	ds_write_b32 v45, v88 offset:3168
	ds_write_b32 v45, v89 offset:3432
	ds_write_b32 v45, v90 offset:3696
	ds_write_b32 v45, v91 offset:3960
	ds_read_b32 v76, v41 offset:8576
	ds_read_b32 v77, v41 offset:8584
	ds_read_b32 v78, v41 offset:8592
	ds_read_b32 v79, v41 offset:8600
	ds_read_b32 v80, v41 offset:8608
	ds_read_b32 v81, v41 offset:8616
	ds_read_b32 v82, v41 offset:8624
	ds_read_b32 v83, v41 offset:8632
	ds_read_b32 v84, v41 offset:8640
	ds_read_b32 v85, v41 offset:8648
	ds_read_b32 v86, v41 offset:8656
	ds_read_b32 v87, v41 offset:8664
	ds_read_b32 v88, v41 offset:8672
	ds_read_b32 v89, v41 offset:8680
	ds_read_b32 v90, v41 offset:8688
	ds_read_b32 v91, v41 offset:8696
	s_waitcnt lgkmcnt(0)
	v_mul_f32_e32 v76, v18, v76
	v_mul_f32_e32 v77, v17, v77
	v_mul_f32_e32 v78, v20, v78
	v_mul_f32_e32 v79, v19, v79
	v_mul_f32_e32 v80, v22, v80
	v_mul_f32_e32 v81, v21, v81
	v_mul_f32_e32 v82, v24, v82
	v_mul_f32_e32 v83, v23, v83
	v_mul_f32_e32 v84, v26, v84
	v_mul_f32_e32 v85, v25, v85
	v_mul_f32_e32 v86, v28, v86
	v_mul_f32_e32 v87, v27, v87
	v_mul_f32_e32 v88, v30, v88
	v_mul_f32_e32 v89, v29, v89
	v_mul_f32_e32 v90, v32, v90
	v_mul_f32_e32 v91, v31, v91
	ds_write_b32 v45, v76 offset:4224
	ds_write_b32 v45, v77 offset:4488
	ds_write_b32 v45, v78 offset:4752
	ds_write_b32 v45, v79 offset:5016
	ds_write_b32 v45, v80 offset:5280
	ds_write_b32 v45, v81 offset:5544
	ds_write_b32 v45, v82 offset:5808
	ds_write_b32 v45, v83 offset:6072
	ds_write_b32 v45, v84 offset:6336
	ds_write_b32 v45, v85 offset:6600
	ds_write_b32 v45, v86 offset:6864
	ds_write_b32 v45, v87 offset:7128
	ds_write_b32 v45, v88 offset:7392
	ds_write_b32 v45, v89 offset:7656
	ds_write_b32 v45, v90 offset:7920
	ds_write_b32 v45, v91 offset:8184
	s_cbranch_execnz .LBB0_43

; __device__ __forceinline__ void tr_load(float (&v)[32], const float* W, int K, int N, int item, int lane) {
;     const int nblk = (N + 31) / 32, kb = item / nblk, nb = item - kb * nblk, k0 = 64 * kb, n0 = 32 * nb;
;     const int nn = n0 + (lane & 31); const bool ok = nn < N;
;     const float* p = W + (size_t)(k0 + (lane >> 5)) * N + (ok ? nn : 0);
; #pragma unroll
;     for (int i = 0; i < 32; ++i) { const float x = __builtin_nontemporal_load(p + (size_t)(2 * i) * N); v[i] = ok ? x : 0.f; }
; }
; __device__ __forceinline__ void prologue_phase(LAS unsigned char* lds) {
;     ...
;             const int nx = it + NGW;
;             if (nx < nitems) { tr_load(v, W, K, N, nx, lane); if (g) gv = g[64 * (nx / nblk) + lane]; }
.LBB0_43:
	s_add_i32 s94, s93, s81
	s_cmp_ge_i32 s94, s89
	s_cselect_b64 s[78:79], -1, 0
	s_and_b64 vcc, exec, s[78:79]
	s_cbranch_vccnz .LBB0_47
	s_abs_i32 s5, s94
	s_mul_hi_u32 s95, s5, s90
	s_mul_i32 s96, s95, s88
	s_sub_i32 s5, s5, s96
	s_ashr_i32 s4, s94, 31
	s_add_i32 s96, s95, 1
	s_sub_i32 s97, s5, s88
	s_cmp_ge_u32 s5, s88
	s_cselect_b32 s95, s96, s95
	s_cselect_b32 s5, s97, s5
	s_add_i32 s96, s95, 1
	s_cmp_ge_u32 s5, s88
	s_cselect_b32 s5, s96, s95
	s_xor_b32 s5, s5, s4
	s_sub_i32 s4, s5, s4
	s_lshl_b32 s95, s4, 6
	s_mul_i32 s4, s91, s4
	s_add_i32 s4, s4, s92
	v_add_u32_e32 v1, s4, v44
	v_or_b32_e32 v2, s95, v39
	s_ashr_i32 s4, s95, 31
	s_mul_i32 s96, s4, s87
	v_mad_u64_u32 v[2:3], s[4:5], v2, s87, 0
	v_cmp_gt_i32_e64 s[4:5], s87, v1
	v_add_u32_e32 v3, s96, v3
	v_lshl_add_u64 v[2:3], v[2:3], 2, s[10:11]
	v_cndmask_b32_e64 v4, 0, v1, s[4:5]
	s_mov_b64 s[2:3], s[4:5]
	v_ashrrev_i32_e32 v5, 31, v4
	v_lshl_add_u64 v[26:27], v[4:5], 2, v[2:3]
	v_lshl_add_u64 v[2:3], s[6:7], 2, v[26:27]
	v_lshl_add_u64 v[4:5], s[70:71], 2, v[26:27]
	v_lshl_add_u64 v[6:7], s[14:15], 2, v[26:27]
	v_lshl_add_u64 v[8:9], s[72:73], 2, v[26:27]
	v_lshl_add_u64 v[10:11], s[16:17], 2, v[26:27]
	v_lshl_add_u64 v[12:13], s[18:19], 2, v[26:27]
	v_lshl_add_u64 v[14:15], s[20:21], 2, v[26:27]
	global_load_dword v1, v[26:27], off nt
	s_nop 0
	global_load_dword v3, v[2:3], off nt
	s_nop 0
	global_load_dword v4, v[4:5], off nt
	s_nop 0
	global_load_dword v5, v[6:7], off nt
	s_nop 0
	global_load_dword v6, v[8:9], off nt
	global_load_dword v7, v[10:11], off nt
	s_nop 0
	global_load_dword v8, v[12:13], off nt
	global_load_dword v9, v[14:15], off nt
	v_lshl_add_u64 v[10:11], s[74:75], 2, v[26:27]
	v_lshl_add_u64 v[12:13], s[22:23], 2, v[26:27]
	v_lshl_add_u64 v[14:15], s[24:25], 2, v[26:27]
	v_lshl_add_u64 v[16:17], s[26:27], 2, v[26:27]
	v_lshl_add_u64 v[18:19], s[28:29], 2, v[26:27]
	v_lshl_add_u64 v[20:21], s[30:31], 2, v[26:27]
	v_lshl_add_u64 v[22:23], s[34:35], 2, v[26:27]
	v_lshl_add_u64 v[24:25], s[36:37], 2, v[26:27]
	global_load_dword v10, v[10:11], off nt
	s_nop 0
	global_load_dword v11, v[12:13], off nt
	s_nop 0
	global_load_dword v12, v[14:15], off nt
	global_load_dword v13, v[16:17], off nt
	s_nop 0
	global_load_dword v14, v[18:19], off nt
	global_load_dword v15, v[20:21], off nt
	global_load_dword v16, v[22:23], off nt
	global_load_dword v17, v[24:25], off nt
	v_lshl_add_u64 v[18:19], s[76:77], 2, v[26:27]
	v_lshl_add_u64 v[20:21], s[38:39], 2, v[26:27]
	v_lshl_add_u64 v[22:23], s[40:41], 2, v[26:27]
	v_lshl_add_u64 v[24:25], s[42:43], 2, v[26:27]
	v_lshl_add_u64 v[28:29], s[44:45], 2, v[26:27]
	v_lshl_add_u64 v[30:31], s[46:47], 2, v[26:27]
	v_lshl_add_u64 v[48:49], s[48:49], 2, v[26:27]
	v_lshl_add_u64 v[50:51], s[50:51], 2, v[26:27]
	global_load_dword v18, v[18:19], off nt
	s_nop 0
	global_load_dword v19, v[20:21], off nt
	s_nop 0
	global_load_dword v20, v[22:23], off nt
	global_load_dword v21, v[24:25], off nt
	s_nop 0
	global_load_dword v22, v[28:29], off nt
	global_load_dword v23, v[30:31], off nt
	global_load_dword v24, v[48:49], off nt
	global_load_dword v25, v[50:51], off nt
	v_lshl_add_u64 v[28:29], s[52:53], 2, v[26:27]
	v_lshl_add_u64 v[30:31], s[54:55], 2, v[26:27]
	v_lshl_add_u64 v[48:49], s[56:57], 2, v[26:27]
	v_lshl_add_u64 v[50:51], s[58:59], 2, v[26:27]
	v_lshl_add_u64 v[52:53], s[60:61], 2, v[26:27]
	v_lshl_add_u64 v[54:55], s[62:63], 2, v[26:27]
	v_lshl_add_u64 v[56:57], s[64:65], 2, v[26:27]
	v_lshl_add_u64 v[58:59], s[66:67], 2, v[26:27]
	global_load_dword v26, v[28:29], off nt
	global_load_dword v27, v[30:31], off nt
	s_nop 0
	global_load_dword v28, v[48:49], off nt
	global_load_dword v29, v[50:51], off nt
	global_load_dword v30, v[52:53], off nt
	global_load_dword v31, v[54:55], off nt
	global_load_dword v32, v[56:57], off nt
	s_nop 0
	global_load_dword v75, v[58:59], off nt
	s_and_b64 vcc, exec, s[0:1]
	s_cbranch_vccnz .LBB0_46
	v_or_b32_e32 v50, s95, v33
	v_ashrrev_i32_e32 v51, 31, v50
	v_lshl_add_u64 v[50:51], v[50:51], 2, s[12:13]
	global_load_dword v46, v[50:51], off
; #define LAS __attribute__((address_space(3)))
; __device__ __forceinline__ void tr_store(bf16_t* WT, int K, int N, LAS float* scr, int item, int lane) {
;     const int nblk = (N + 31) / 32, kb = item / nblk, nb = item - kb * nblk, k0 = 64 * kb, n0 = 32 * nb;
;     const int c = lane & 7;
; #pragma unroll
;     for (int j = 0; j < 4; ++j) { const int n = (lane >> 3) + 8 * j; const LAS float* s = scr + (8 * c) * 33 + n;
;         v4u o; o.x = pkbf(s[0 * 33], s[1 * 33]); o.y = pkbf(s[2 * 33], s[3 * 33]); o.z = pkbf(s[4 * 33], s[5 * 33]); o.w = pkbf(s[6 * 33], s[7 * 33]);
;         *(v4u*)(WT + (size_t)(n0 + n) * K + k0 + 8 * c) = o; }
; }
; __device__ __forceinline__ void prologue_phase(LAS unsigned char* lds) {
;     ...
;             const int nx = it + NGW;
;             if (nx < nitems) { tr_load(v, W, K, N, nx, lane); if (g) gv = g[64 * (nx / nblk) + lane]; }
;             asm volatile("s_waitcnt lgkmcnt(0)" ::: "memory");
;             tr_store(WT, K, N, scr, it, lane);
;             asm volatile("s_waitcnt lgkmcnt(0)" ::: "memory");
.LBB0_46:
.LBB0_47:
	s_abs_i32 s1, s93
	s_mul_hi_u32 s4, s1, s90
	s_mul_i32 s5, s4, s88
	s_sub_i32 s1, s1, s5
	s_ashr_i32 s0, s93, 31
	s_add_i32 s5, s4, 1
	s_sub_i32 s93, s1, s88
	s_cmp_ge_u32 s1, s88
	s_cselect_b32 s4, s5, s4
	s_cselect_b32 s1, s93, s1
	s_add_i32 s5, s4, 1
	s_cmp_ge_u32 s1, s88
	s_cselect_b32 s1, s5, s4
	s_xor_b32 s1, s1, s0
	s_sub_i32 s4, s1, s0
	s_lshl_b32 s0, s4, 6
	s_ashr_i32 s1, s0, 31
	v_lshl_add_u64 v[68:69], s[0:1], 1, v[36:37]
	s_mul_i32 s0, s91, s4
	s_waitcnt lgkmcnt(0)
	s_add_i32 s0, s0, s84
	ds_read2_b32 v[52:53], v42 offset0:33 offset1:41
	ds_read2_b32 v[54:55], v42 offset1:8
	ds_read2_b32 v[56:57], v42 offset0:66 offset1:74
	ds_read2_b32 v[58:59], v42 offset0:99 offset1:107
	ds_read2_b32 v[60:61], v42 offset0:132 offset1:140
	ds_read2_b32 v[62:63], v42 offset0:165 offset1:173
	ds_read2_b32 v[64:65], v42 offset0:198 offset1:206
	ds_read2_b32 v[66:67], v42 offset0:231 offset1:239
	v_add_u32_e32 v74, s0, v47
	v_mad_u64_u32 v[70:71], s[0:1], v74, s9, 0
	s_waitcnt lgkmcnt(6)
	v_cvt_pk_bf16_f32 v48, v54, v52
	v_ashrrev_i32_e32 v54, 31, v74
	v_mov_b32_e32 v52, v71
	v_mad_u64_u32 v[72:73], s[0:1], v54, s9, v[52:53]
	v_mov_b32_e32 v71, v72
	s_waitcnt lgkmcnt(4)
	v_cvt_pk_bf16_f32 v49, v56, v58
	s_waitcnt lgkmcnt(2)
	v_cvt_pk_bf16_f32 v50, v60, v62
	s_waitcnt lgkmcnt(0)
	v_cvt_pk_bf16_f32 v51, v64, v66
	v_lshl_add_u64 v[70:71], v[70:71], 1, v[68:69]
	v_add_u32_e32 v52, 8, v74
	global_store_dwordx4 v[70:71], v[48:51], off
	v_add_u32_e32 v47, s85, v47
	s_andn2_b64 vcc, exec, s[78:79]
	v_cvt_pk_bf16_f32 v48, v55, v53
	v_ashrrev_i32_e32 v55, 31, v52
	v_mad_u64_u32 v[52:53], s[0:1], v52, s9, 0
	v_mov_b32_e32 v54, v53
	v_mad_u64_u32 v[54:55], s[0:1], v55, s9, v[54:55]
	v_mov_b32_e32 v53, v54
	v_cvt_pk_bf16_f32 v49, v57, v59
	v_cvt_pk_bf16_f32 v50, v61, v63
	v_cvt_pk_bf16_f32 v51, v65, v67
	v_lshl_add_u64 v[52:53], v[52:53], 1, v[68:69]
	ds_read2_b32 v[54:55], v42 offset0:16 offset1:24
	ds_read2_b32 v[56:57], v42 offset0:49 offset1:57
	ds_read2_b32 v[58:59], v42 offset0:82 offset1:90
	ds_read2_b32 v[60:61], v42 offset0:115 offset1:123
	ds_read2_b32 v[62:63], v42 offset0:148 offset1:156
	ds_read2_b32 v[64:65], v42 offset0:181 offset1:189
	ds_read2_b32 v[66:67], v42 offset0:214 offset1:222
	ds_read2_b32 v[70:71], v42 offset0:247 offset1:255
	global_store_dwordx4 v[52:53], v[48:51], off
	v_add_u32_e32 v52, 16, v74
	s_add_i32 s92, s92, s85
	s_waitcnt lgkmcnt(6)
	v_cvt_pk_bf16_f32 v48, v54, v56
	v_ashrrev_i32_e32 v56, 31, v52
	v_mad_u64_u32 v[52:53], s[0:1], v52, s9, 0
	v_mov_b32_e32 v54, v53
	v_mad_u64_u32 v[72:73], s[0:1], v56, s9, v[54:55]
	v_mov_b32_e32 v53, v72
	s_waitcnt lgkmcnt(4)
	v_cvt_pk_bf16_f32 v49, v58, v60
	s_waitcnt lgkmcnt(2)
	v_cvt_pk_bf16_f32 v50, v62, v64
	s_waitcnt lgkmcnt(0)
	v_cvt_pk_bf16_f32 v51, v66, v70
	v_lshl_add_u64 v[52:53], v[52:53], 1, v[68:69]
	global_store_dwordx4 v[52:53], v[48:51], off
	v_add_u32_e32 v52, 24, v74
	s_nop 0
	v_cvt_pk_bf16_f32 v48, v55, v57
	v_ashrrev_i32_e32 v55, 31, v52
	v_mad_u64_u32 v[52:53], s[0:1], v52, s9, 0
	v_mov_b32_e32 v54, v53
	v_mad_u64_u32 v[54:55], s[0:1], v55, s9, v[54:55]
	v_mov_b32_e32 v53, v54
	v_cvt_pk_bf16_f32 v49, v59, v61
	v_cvt_pk_bf16_f32 v50, v63, v65
	v_cvt_pk_bf16_f32 v51, v67, v71
	v_lshl_add_u64 v[52:53], v[52:53], 1, v[68:69]
	global_store_dwordx4 v[52:53], v[48:51], off
	s_waitcnt lgkmcnt(0)
	s_cbranch_vccz .LBB0_6
	s_waitcnt vmcnt(35)
	v_cndmask_b32_e64 v2, 0, v1, s[2:3]
	s_waitcnt vmcnt(34)
	v_cndmask_b32_e64 v1, 0, v3, s[2:3]
	s_waitcnt vmcnt(33)
	v_cndmask_b32_e64 v4, 0, v4, s[2:3]
	s_waitcnt vmcnt(32)
	v_cndmask_b32_e64 v3, 0, v5, s[2:3]
	s_waitcnt vmcnt(31)
	v_cndmask_b32_e64 v6, 0, v6, s[2:3]
	s_waitcnt vmcnt(30)
	v_cndmask_b32_e64 v5, 0, v7, s[2:3]
	s_waitcnt vmcnt(29)
	v_cndmask_b32_e64 v8, 0, v8, s[2:3]
	s_waitcnt vmcnt(28)
	v_cndmask_b32_e64 v7, 0, v9, s[2:3]
	s_waitcnt vmcnt(27)
	v_cndmask_b32_e64 v10, 0, v10, s[2:3]
	s_waitcnt vmcnt(26)
	v_cndmask_b32_e64 v9, 0, v11, s[2:3]
	s_waitcnt vmcnt(25)
	v_cndmask_b32_e64 v12, 0, v12, s[2:3]
	s_waitcnt vmcnt(24)
	v_cndmask_b32_e64 v11, 0, v13, s[2:3]
	s_waitcnt vmcnt(23)
	v_cndmask_b32_e64 v14, 0, v14, s[2:3]
	s_waitcnt vmcnt(22)
	v_cndmask_b32_e64 v13, 0, v15, s[2:3]
	s_waitcnt vmcnt(21)
	v_cndmask_b32_e64 v16, 0, v16, s[2:3]
	s_waitcnt vmcnt(20)
	v_cndmask_b32_e64 v15, 0, v17, s[2:3]
	s_waitcnt vmcnt(19)
	v_cndmask_b32_e64 v18, 0, v18, s[2:3]
	s_waitcnt vmcnt(18)
	v_cndmask_b32_e64 v17, 0, v19, s[2:3]
	s_waitcnt vmcnt(17)
	v_cndmask_b32_e64 v20, 0, v20, s[2:3]
	s_waitcnt vmcnt(16)
	v_cndmask_b32_e64 v19, 0, v21, s[2:3]
	s_waitcnt vmcnt(15)
	v_cndmask_b32_e64 v22, 0, v22, s[2:3]
	s_waitcnt vmcnt(14)
	v_cndmask_b32_e64 v21, 0, v23, s[2:3]
	s_waitcnt vmcnt(13)
	v_cndmask_b32_e64 v24, 0, v24, s[2:3]
	s_waitcnt vmcnt(12)
	v_cndmask_b32_e64 v23, 0, v25, s[2:3]
	s_waitcnt vmcnt(11)
	v_cndmask_b32_e64 v26, 0, v26, s[2:3]
	s_waitcnt vmcnt(10)
	v_cndmask_b32_e64 v25, 0, v27, s[2:3]
	s_waitcnt vmcnt(9)
	v_cndmask_b32_e64 v28, 0, v28, s[2:3]
	s_waitcnt vmcnt(8)
	v_cndmask_b32_e64 v27, 0, v29, s[2:3]
	s_waitcnt vmcnt(7)
	v_cndmask_b32_e64 v30, 0, v30, s[2:3]
	s_waitcnt vmcnt(6)
	v_cndmask_b32_e64 v29, 0, v31, s[2:3]
	s_waitcnt vmcnt(5)
	v_cndmask_b32_e64 v32, 0, v32, s[2:3]
	s_waitcnt vmcnt(4)
	v_cndmask_b32_e64 v31, 0, v75, s[2:3]
	s_mov_b32 s93, s94
	v_cndmask_b32_e64 v48, 0, 1, s[68:69]
	v_cmp_ne_u32_e64 s[0:1], 1, v48
	s_andn2_b64 vcc, exec, s[68:69]
	s_cbranch_vccz .LBB0_41
